# RWKV pass-1 inner scan remapped: 4 waves, each lane holds a 16-column segment of both the U and P state rows (fewer cross-lane reduction ops per step); other 4 waves idle at the barrier during the 32-
# speedup vs baseline: 1.0310x; 1.0022x over previous
; template <int PASS>
; __device__ __forceinline__ void rwkv_scan_phase(const bf16* Z, const RwkvW w, const bf16* Wl, float* Pb, float* Ub, bf16* MIX, bf16* RHO, float* BON, unsigned char* lds) {
;     ...
;         if (PASS == 1) { float* du = Ub + ((size_t)u * 64 + rp) * 64 + j0; float* dp = Pb + ((size_t)u * 64 + rp) * 64 + j0;
;             *(f32x4*)du = (f32x4){(float)SU[0][0], (float)SU[0][1], (float)SU[1][0], (float)SU[1][1]}; *(f32x4*)(du + 4) = (f32x4){(float)SU[2][0], (float)SU[2][1], (float)SU[3][0], (float)SU[3][1]};
;             *(f32x4*)dp = (f32x4){(float)SP[0][0], (float)SP[0][1], (float)SP[1][0], (float)SP[1][1]}; *(f32x4*)(dp + 4) = (f32x4){(float)SP[2][0], (float)SP[2][1], (float)SP[3][0], (float)SP[3][1]}; }
.LBB0_431:
	s_lshl_b64 s[6:7], s[14:15], 12
	v_lshrrev_b32_e32 v59, 2, v162
	v_and_b32_e32 v58, 3, v162
	v_lshlrev_b32_e32 v59, 6, v59
	v_lshl_or_b32 v2, v58, 4, v59
	v_and_b32_e32 v58, 7, v162
	v_lshlrev_b32_e32 v58, 3, v58
	v_sub_u32_e32 v2, v2, v58
	v_mov_b32_e32 v3, 0
	v_cmp_gt_u32_e32 vcc, 0x100, v162
	v_lshl_add_u64 v[2:3], s[6:7], 0, v[2:3]
	v_lshlrev_b64 v[2:3], 2, v[2:3]
	v_lshl_add_u64 v[6:7], v[108:109], 0, v[2:3]
	v_lshl_add_u64 v[8:9], v[110:111], 0, v[2:3]
	s_and_saveexec_b64 s[98:99], vcc
	v_cvt_f32_f16_sdwa v3, v113 dst_sel:DWORD dst_unused:UNUSED_PAD src0_sel:WORD_1
	v_cvt_f32_f16_e32 v2, v113
	v_cvt_f32_f16_sdwa v5, v178 dst_sel:DWORD dst_unused:UNUSED_PAD src0_sel:WORD_1
	v_cvt_f32_f16_e32 v4, v178
	global_store_dwordx4 v[6:7], v[2:5], off
	s_nop 1
	v_cvt_f32_f16_sdwa v3, v177 dst_sel:DWORD dst_unused:UNUSED_PAD src0_sel:WORD_1
	v_cvt_f32_f16_e32 v2, v177
	v_cvt_f32_f16_sdwa v5, v176 dst_sel:DWORD dst_unused:UNUSED_PAD src0_sel:WORD_1
	v_cvt_f32_f16_e32 v4, v176
	global_store_dwordx4 v[6:7], v[2:5], off offset:16
	s_nop 1
	v_cvt_f32_f16_sdwa v3, v175 dst_sel:DWORD dst_unused:UNUSED_PAD src0_sel:WORD_1
	v_cvt_f32_f16_e32 v2, v175
	v_cvt_f32_f16_sdwa v5, v174 dst_sel:DWORD dst_unused:UNUSED_PAD src0_sel:WORD_1
	v_cvt_f32_f16_e32 v4, v174
	global_store_dwordx4 v[6:7], v[2:5], off offset:32
	s_nop 1
	v_cvt_f32_f16_sdwa v3, v161 dst_sel:DWORD dst_unused:UNUSED_PAD src0_sel:WORD_1
	v_cvt_f32_f16_e32 v2, v161
	v_cvt_f32_f16_sdwa v5, v160 dst_sel:DWORD dst_unused:UNUSED_PAD src0_sel:WORD_1
	v_cvt_f32_f16_e32 v4, v160
	global_store_dwordx4 v[6:7], v[2:5], off offset:48
	s_nop 1
	v_cvt_f32_f16_sdwa v3, v228 dst_sel:DWORD dst_unused:UNUSED_PAD src0_sel:WORD_1
	v_cvt_f32_f16_e32 v2, v228
	v_cvt_f32_f16_sdwa v5, v229 dst_sel:DWORD dst_unused:UNUSED_PAD src0_sel:WORD_1
	v_cvt_f32_f16_e32 v4, v229
	global_store_dwordx4 v[8:9], v[2:5], off
	s_nop 1
	v_cvt_f32_f16_sdwa v3, v230 dst_sel:DWORD dst_unused:UNUSED_PAD src0_sel:WORD_1
	v_cvt_f32_f16_e32 v2, v230
	v_cvt_f32_f16_sdwa v5, v231 dst_sel:DWORD dst_unused:UNUSED_PAD src0_sel:WORD_1
	v_cvt_f32_f16_e32 v4, v231
	global_store_dwordx4 v[8:9], v[2:5], off offset:16
	s_nop 1
	v_cvt_f32_f16_sdwa v3, v232 dst_sel:DWORD dst_unused:UNUSED_PAD src0_sel:WORD_1
	v_cvt_f32_f16_e32 v2, v232
	v_cvt_f32_f16_sdwa v5, v233 dst_sel:DWORD dst_unused:UNUSED_PAD src0_sel:WORD_1
	v_cvt_f32_f16_e32 v4, v233
	global_store_dwordx4 v[8:9], v[2:5], off offset:32
	s_nop 1
	v_cvt_f32_f16_sdwa v3, v234 dst_sel:DWORD dst_unused:UNUSED_PAD src0_sel:WORD_1
	v_cvt_f32_f16_e32 v2, v234
	v_cvt_f32_f16_sdwa v5, v235 dst_sel:DWORD dst_unused:UNUSED_PAD src0_sel:WORD_1
	v_cvt_f32_f16_e32 v4, v235
	global_store_dwordx4 v[8:9], v[2:5], off offset:48
	s_nop 1
	s_or_b64 exec, exec, s[98:99]
	s_add_i32 s14, s14, s70
	s_cmpk_gt_i32 s14, 0xff
	s_cbranch_scc1 .LBB0_455

; template <int PASS>
; __device__ __forceinline__ void rwkv_scan_phase(const bf16* Z, const RwkvW w, const bf16* Wl, float* Pb, float* Ub, bf16* MIX, bf16* RHO, float* BON, unsigned char* lds) {
;     ...
;         h2 SU[4], SP[4];
;         if (PASS == 1) {
; #pragma unroll
;             for (int x = 0; x < 4; ++x) { SU[x] = (h2){(_Float16)0.f, (_Float16)0.f}; SP[x] = (h2){(_Float16)((rp == j0 + 2 * x) ? 1.f : 0.f), (_Float16)((rp == j0 + 2 * x + 1) ? 1.f : 0.f)}; }
.LBB0_434:
	s_or_b64 exec, exec, s[28:29]
	s_lshl_b32 s28, s30, 2
	s_add_u32 s28, s34, s28
	v_lshl_add_u64 v[130:131], s[16:17], 0, v[0:1]
	v_lshl_add_u64 v[134:135], s[4:5], 0, v[0:1]
	s_addc_u32 s29, s35, 0
	s_mov_b32 s36, 0
	v_lshrrev_b32_e32 v59, 2, v162
	v_and_b32_e32 v58, 3, v162
	v_lshlrev_b32_e32 v58, 4, v58
	v_sub_u32_e32 v59, v59, v58
	v_cmp_gt_u32_e32 vcc, 0x100, v162
	v_mov_b32_e32 v60, 0x3c000000
	s_nop 0
	v_cndmask_b32_e32 v59, -1, v59, vcc
	v_mov_b32_e32 v113, 0
	v_cmp_eq_u32_e32 vcc, 0, v59
	s_nop 1
	v_cndmask_b32_e32 v228, 0, v171, vcc
	v_cmp_eq_u32_e32 vcc, 1, v59
	s_nop 1
	v_cndmask_b32_e32 v228, v228, v60, vcc
	v_mov_b32_e32 v178, 0
	v_cmp_eq_u32_e32 vcc, 2, v59
	s_nop 1
	v_cndmask_b32_e32 v229, 0, v171, vcc
	v_cmp_eq_u32_e32 vcc, 3, v59
	s_nop 1
	v_cndmask_b32_e32 v229, v229, v60, vcc
	v_mov_b32_e32 v177, 0
	v_cmp_eq_u32_e32 vcc, 4, v59
	s_nop 1
	v_cndmask_b32_e32 v230, 0, v171, vcc
	v_cmp_eq_u32_e32 vcc, 5, v59
	s_nop 1
	v_cndmask_b32_e32 v230, v230, v60, vcc
	v_mov_b32_e32 v176, 0
	v_cmp_eq_u32_e32 vcc, 6, v59
	s_nop 1
	v_cndmask_b32_e32 v231, 0, v171, vcc
	v_cmp_eq_u32_e32 vcc, 7, v59
	s_nop 1
	v_cndmask_b32_e32 v231, v231, v60, vcc
	v_mov_b32_e32 v175, 0
	v_cmp_eq_u32_e32 vcc, 8, v59
	s_nop 1
	v_cndmask_b32_e32 v232, 0, v171, vcc
	v_cmp_eq_u32_e32 vcc, 9, v59
	s_nop 1
	v_cndmask_b32_e32 v232, v232, v60, vcc
	v_mov_b32_e32 v174, 0
	v_cmp_eq_u32_e32 vcc, 10, v59
	s_nop 1
	v_cndmask_b32_e32 v233, 0, v171, vcc
	v_cmp_eq_u32_e32 vcc, 11, v59
	s_nop 1
	v_cndmask_b32_e32 v233, v233, v60, vcc
	v_mov_b32_e32 v161, 0
	v_cmp_eq_u32_e32 vcc, 12, v59
	s_nop 1
	v_cndmask_b32_e32 v234, 0, v171, vcc
	v_cmp_eq_u32_e32 vcc, 13, v59
	s_nop 1
	v_cndmask_b32_e32 v234, v234, v60, vcc
	v_mov_b32_e32 v160, 0
	v_cmp_eq_u32_e32 vcc, 14, v59
	s_nop 1
	v_cndmask_b32_e32 v235, 0, v171, vcc
	v_cmp_eq_u32_e32 vcc, 15, v59
	s_nop 1
	v_cndmask_b32_e32 v235, v235, v60, vcc

.LBB0_441:
	v_readfirstlane_b32 s100, v162
	v_and_b32_e32 v202, 3, v162
	v_cmp_eq_u32_e64 s[98:99], 0, v202
	v_lshlrev_b32_e32 v202, 5, v202
	v_bfe_u32 v203, v162, 2, 6
	v_add_u32_e32 v202, s39, v202
	v_lshl_add_u32 v203, v203, 2, s39
	s_lshr_b32 s100, s100, 8
	s_cmp_eq_u32 s100, 0
	s_cbranch_scc0 .LBB0_451
	s_mov_b32 s37, 0
	ds_read_b128 v[82:85], v202 offset:4096
	ds_read_b128 v[86:89], v202 offset:4112
	ds_read_b128 v[58:61], v202 offset:0
	ds_read_b128 v[62:65], v202 offset:16
	ds_read_b128 v[182:185], v202 offset:16384
	ds_read_b128 v[186:189], v202 offset:16400
	ds_read_b128 v[66:69], v202 offset:8192
	ds_read_b128 v[70:73], v202 offset:8208
	ds_read_b128 v[74:77], v202 offset:12288
	ds_read_b128 v[78:81], v202 offset:12304
	ds_read_b32 v115, v203 offset:20480
	s_waitcnt lgkmcnt(7)
	ds_read_b128 v[90:93], v202 offset:4224
	ds_read_b128 v[94:97], v202 offset:4240
	v_dot2_f32_f16 v198, v113, v58, 0
	v_dot2_f32_f16 v199, v228, v58, 0
	v_dot2_f32_f16 v198, v178, v59, v198
	v_dot2_f32_f16 v199, v229, v59, v199
	v_dot2_f32_f16 v198, v177, v60, v198
	v_dot2_f32_f16 v199, v230, v60, v199
	v_dot2_f32_f16 v198, v176, v61, v198
	v_dot2_f32_f16 v199, v231, v61, v199
	v_dot2_f32_f16 v198, v175, v62, v198
	v_dot2_f32_f16 v199, v232, v62, v199
	v_dot2_f32_f16 v198, v174, v63, v198
	v_dot2_f32_f16 v199, v233, v63, v199
	v_dot2_f32_f16 v198, v161, v64, v198
	v_dot2_f32_f16 v199, v234, v64, v199
	v_dot2_f32_f16 v198, v160, v65, v198
	v_dot2_f32_f16 v199, v235, v65, v199
	ds_read_b128 v[58:61], v202 offset:128
	ds_read_b128 v[62:65], v202 offset:144
	ds_read_b128 v[190:193], v202 offset:16512
	ds_read_b128 v[194:197], v202 offset:16528
	v_add_f32_dpp v198, v198, v198 quad_perm:[1,0,3,2] row_mask:0xf bank_mask:0xf bound_ctrl:1
	v_add_f32_dpp v199, v199, v199 quad_perm:[1,0,3,2] row_mask:0xf bank_mask:0xf bound_ctrl:1
	s_waitcnt lgkmcnt(9)
	v_pk_mul_f16 v113, v113, v66
	v_pk_mul_f16 v178, v178, v67
	v_pk_mul_f16 v177, v177, v68
	v_pk_mul_f16 v176, v176, v69
	v_pk_mul_f16 v175, v175, v70
	v_pk_mul_f16 v174, v174, v71
	v_pk_mul_f16 v161, v161, v72
	v_pk_mul_f16 v160, v160, v73
	v_pk_mul_f16 v228, v228, v66
	v_pk_mul_f16 v229, v229, v67
	v_pk_mul_f16 v230, v230, v68
	v_pk_mul_f16 v231, v231, v69
	v_pk_mul_f16 v232, v232, v70
	v_pk_mul_f16 v233, v233, v71
	v_pk_mul_f16 v234, v234, v72
	v_pk_mul_f16 v235, v235, v73
	v_add_f32_dpp v198, v198, v198 quad_perm:[2,3,0,1] row_mask:0xf bank_mask:0xf bound_ctrl:1
	v_add_f32_dpp v199, v199, v199 quad_perm:[2,3,0,1] row_mask:0xf bank_mask:0xf bound_ctrl:1
	s_waitcnt lgkmcnt(6)
	v_pk_fma_f16 v113, v115, v74, v113
	v_pk_fma_f16 v178, v115, v75, v178
	v_pk_fma_f16 v177, v115, v76, v177
	v_pk_fma_f16 v176, v115, v77, v176
	v_pk_fma_f16 v175, v115, v78, v175
	v_pk_fma_f16 v174, v115, v79, v174
	v_pk_fma_f16 v161, v115, v80, v161
	v_pk_fma_f16 v160, v115, v81, v160
	ds_read_b128 v[66:69], v202 offset:8320
	ds_read_b128 v[70:73], v202 offset:8336
	ds_read_b128 v[74:77], v202 offset:12416
	ds_read_b128 v[78:81], v202 offset:12432
	ds_read_b32 v115, v203 offset:20736
	v_cvt_pk_f16_f32 v198, v198, v199
	s_waitcnt lgkmcnt(15)
	v_pk_fma_f16 v113, v198, v82, v113 op_sel_hi:[0,1,1]
	v_pk_fma_f16 v228, v198, v82, v228 op_sel:[1,0,0] op_sel_hi:[1,1,1]
	v_pk_fma_f16 v178, v198, v83, v178 op_sel_hi:[0,1,1]
	v_pk_fma_f16 v229, v198, v83, v229 op_sel:[1,0,0] op_sel_hi:[1,1,1]
	v_pk_fma_f16 v177, v198, v84, v177 op_sel_hi:[0,1,1]
	v_pk_fma_f16 v230, v198, v84, v230 op_sel:[1,0,0] op_sel_hi:[1,1,1]
	v_pk_fma_f16 v176, v198, v85, v176 op_sel_hi:[0,1,1]
	v_pk_fma_f16 v231, v198, v85, v231 op_sel:[1,0,0] op_sel_hi:[1,1,1]
	v_pk_fma_f16 v175, v198, v86, v175 op_sel_hi:[0,1,1]
	v_pk_fma_f16 v232, v198, v86, v232 op_sel:[1,0,0] op_sel_hi:[1,1,1]
	v_pk_fma_f16 v174, v198, v87, v174 op_sel_hi:[0,1,1]
	v_pk_fma_f16 v233, v198, v87, v233 op_sel:[1,0,0] op_sel_hi:[1,1,1]
	v_pk_fma_f16 v161, v198, v88, v161 op_sel_hi:[0,1,1]
	v_pk_fma_f16 v234, v198, v88, v234 op_sel:[1,0,0] op_sel_hi:[1,1,1]
	v_pk_fma_f16 v160, v198, v89, v160 op_sel_hi:[0,1,1]
	v_pk_fma_f16 v235, v198, v89, v235 op_sel:[1,0,0] op_sel_hi:[1,1,1]
.LscanH_loop:
	s_waitcnt lgkmcnt(7)
	ds_read_b128 v[82:85], v202 offset:4352
	ds_read_b128 v[86:89], v202 offset:4368
	v_dot2_f32_f16 v198, v113, v58, 0
	v_dot2_f32_f16 v199, v228, v58, 0
	v_dot2_f32_f16 v200, v113, v182, 0
	v_dot2_f32_f16 v201, v228, v182, 0
	v_dot2_f32_f16 v198, v178, v59, v198
	v_dot2_f32_f16 v199, v229, v59, v199
	v_dot2_f32_f16 v200, v178, v183, v200
	v_dot2_f32_f16 v201, v229, v183, v201
	v_dot2_f32_f16 v198, v177, v60, v198
	v_dot2_f32_f16 v199, v230, v60, v199
	v_dot2_f32_f16 v200, v177, v184, v200
	v_dot2_f32_f16 v201, v230, v184, v201
	v_dot2_f32_f16 v198, v176, v61, v198
	v_dot2_f32_f16 v199, v231, v61, v199
	v_dot2_f32_f16 v200, v176, v185, v200
	v_dot2_f32_f16 v201, v231, v185, v201
	v_dot2_f32_f16 v198, v175, v62, v198
	v_dot2_f32_f16 v199, v232, v62, v199
	v_dot2_f32_f16 v200, v175, v186, v200
	v_dot2_f32_f16 v201, v232, v186, v201
	v_dot2_f32_f16 v198, v174, v63, v198
	v_dot2_f32_f16 v199, v233, v63, v199
	v_dot2_f32_f16 v200, v174, v187, v200
	v_dot2_f32_f16 v201, v233, v187, v201
	v_dot2_f32_f16 v198, v161, v64, v198
	v_dot2_f32_f16 v199, v234, v64, v199
	v_dot2_f32_f16 v200, v161, v188, v200
	v_dot2_f32_f16 v201, v234, v188, v201
	v_dot2_f32_f16 v198, v160, v65, v198
	v_dot2_f32_f16 v199, v235, v65, v199
	v_dot2_f32_f16 v200, v160, v189, v200
	v_dot2_f32_f16 v201, v235, v189, v201
	ds_read_b128 v[58:61], v202 offset:256
	ds_read_b128 v[62:65], v202 offset:272
	ds_read_b128 v[182:185], v202 offset:16640
	ds_read_b128 v[186:189], v202 offset:16656
	v_add_f32_dpp v198, v198, v198 quad_perm:[1,0,3,2] row_mask:0xf bank_mask:0xf bound_ctrl:1
	v_add_f32_dpp v199, v199, v199 quad_perm:[1,0,3,2] row_mask:0xf bank_mask:0xf bound_ctrl:1
	v_add_f32_dpp v200, v200, v200 quad_perm:[1,0,3,2] row_mask:0xf bank_mask:0xf bound_ctrl:1
	v_add_f32_dpp v201, v201, v201 quad_perm:[1,0,3,2] row_mask:0xf bank_mask:0xf bound_ctrl:1
	s_waitcnt lgkmcnt(9)
	v_pk_mul_f16 v113, v113, v66
	v_pk_mul_f16 v178, v178, v67
	v_pk_mul_f16 v177, v177, v68
	v_pk_mul_f16 v176, v176, v69
	v_pk_mul_f16 v175, v175, v70
	v_pk_mul_f16 v174, v174, v71
	v_pk_mul_f16 v161, v161, v72
	v_pk_mul_f16 v160, v160, v73
	v_pk_mul_f16 v228, v228, v66
	v_pk_mul_f16 v229, v229, v67
	v_pk_mul_f16 v230, v230, v68
	v_pk_mul_f16 v231, v231, v69
	v_pk_mul_f16 v232, v232, v70
	v_pk_mul_f16 v233, v233, v71
	v_pk_mul_f16 v234, v234, v72
	v_pk_mul_f16 v235, v235, v73
	v_add_f32_dpp v198, v198, v198 quad_perm:[2,3,0,1] row_mask:0xf bank_mask:0xf bound_ctrl:1
	v_add_f32_dpp v199, v199, v199 quad_perm:[2,3,0,1] row_mask:0xf bank_mask:0xf bound_ctrl:1
	v_add_f32_dpp v200, v200, v200 quad_perm:[2,3,0,1] row_mask:0xf bank_mask:0xf bound_ctrl:1
	v_add_f32_dpp v201, v201, v201 quad_perm:[2,3,0,1] row_mask:0xf bank_mask:0xf bound_ctrl:1
	s_waitcnt lgkmcnt(6)
	v_pk_fma_f16 v113, v115, v74, v113
	v_pk_fma_f16 v178, v115, v75, v178
	v_pk_fma_f16 v177, v115, v76, v177
	v_pk_fma_f16 v176, v115, v77, v176
	v_pk_fma_f16 v175, v115, v78, v175
	v_pk_fma_f16 v174, v115, v79, v174
	v_pk_fma_f16 v161, v115, v80, v161
	v_pk_fma_f16 v160, v115, v81, v160
	ds_read_b128 v[66:69], v202 offset:8448
	ds_read_b128 v[70:73], v202 offset:8464
	ds_read_b128 v[74:77], v202 offset:12544
	ds_read_b128 v[78:81], v202 offset:12560
	ds_read_b32 v115, v203 offset:20992
	v_cvt_pk_f16_f32 v198, v198, v199
	s_waitcnt lgkmcnt(15)
	v_pk_fma_f16 v113, v198, v90, v113 op_sel_hi:[0,1,1]
	v_pk_fma_f16 v228, v198, v90, v228 op_sel:[1,0,0] op_sel_hi:[1,1,1]
	v_pk_fma_f16 v178, v198, v91, v178 op_sel_hi:[0,1,1]
	v_pk_fma_f16 v229, v198, v91, v229 op_sel:[1,0,0] op_sel_hi:[1,1,1]
	v_pk_fma_f16 v177, v198, v92, v177 op_sel_hi:[0,1,1]
	v_pk_fma_f16 v230, v198, v92, v230 op_sel:[1,0,0] op_sel_hi:[1,1,1]
	v_pk_fma_f16 v176, v198, v93, v176 op_sel_hi:[0,1,1]
	v_pk_fma_f16 v231, v198, v93, v231 op_sel:[1,0,0] op_sel_hi:[1,1,1]
	v_pk_fma_f16 v175, v198, v94, v175 op_sel_hi:[0,1,1]
	v_pk_fma_f16 v232, v198, v94, v232 op_sel:[1,0,0] op_sel_hi:[1,1,1]
	v_pk_fma_f16 v174, v198, v95, v174 op_sel_hi:[0,1,1]
	v_pk_fma_f16 v233, v198, v95, v233 op_sel:[1,0,0] op_sel_hi:[1,1,1]
	v_pk_fma_f16 v161, v198, v96, v161 op_sel_hi:[0,1,1]
	v_pk_fma_f16 v234, v198, v96, v234 op_sel:[1,0,0] op_sel_hi:[1,1,1]
	v_pk_fma_f16 v160, v198, v97, v160 op_sel_hi:[0,1,1]
	v_pk_fma_f16 v235, v198, v97, v235 op_sel:[1,0,0] op_sel_hi:[1,1,1]
	s_and_saveexec_b64 s[30:31], s[98:99]
	ds_write2st64_b32 v203, v201, v200 offset0:112 offset1:144
	s_or_b64 exec, exec, s[30:31]
	s_waitcnt lgkmcnt(8)
	ds_read_b128 v[90:93], v202 offset:4480
	ds_read_b128 v[94:97], v202 offset:4496
	v_dot2_f32_f16 v198, v113, v58, 0
	v_dot2_f32_f16 v199, v228, v58, 0
	v_dot2_f32_f16 v200, v113, v190, 0
	v_dot2_f32_f16 v201, v228, v190, 0
	v_dot2_f32_f16 v198, v178, v59, v198
	v_dot2_f32_f16 v199, v229, v59, v199
	v_dot2_f32_f16 v200, v178, v191, v200
	v_dot2_f32_f16 v201, v229, v191, v201
	v_dot2_f32_f16 v198, v177, v60, v198
	v_dot2_f32_f16 v199, v230, v60, v199
	v_dot2_f32_f16 v200, v177, v192, v200
	v_dot2_f32_f16 v201, v230, v192, v201
	v_dot2_f32_f16 v198, v176, v61, v198
	v_dot2_f32_f16 v199, v231, v61, v199
	v_dot2_f32_f16 v200, v176, v193, v200
	v_dot2_f32_f16 v201, v231, v193, v201
	v_dot2_f32_f16 v198, v175, v62, v198
	v_dot2_f32_f16 v199, v232, v62, v199
	v_dot2_f32_f16 v200, v175, v194, v200
	v_dot2_f32_f16 v201, v232, v194, v201
	v_dot2_f32_f16 v198, v174, v63, v198
	v_dot2_f32_f16 v199, v233, v63, v199
	v_dot2_f32_f16 v200, v174, v195, v200
	v_dot2_f32_f16 v201, v233, v195, v201
	v_dot2_f32_f16 v198, v161, v64, v198
	v_dot2_f32_f16 v199, v234, v64, v199
	v_dot2_f32_f16 v200, v161, v196, v200
	v_dot2_f32_f16 v201, v234, v196, v201
	v_dot2_f32_f16 v198, v160, v65, v198
	v_dot2_f32_f16 v199, v235, v65, v199
	v_dot2_f32_f16 v200, v160, v197, v200
	v_dot2_f32_f16 v201, v235, v197, v201
	ds_read_b128 v[58:61], v202 offset:384
	ds_read_b128 v[62:65], v202 offset:400
	ds_read_b128 v[190:193], v202 offset:16768
	ds_read_b128 v[194:197], v202 offset:16784
	v_add_f32_dpp v198, v198, v198 quad_perm:[1,0,3,2] row_mask:0xf bank_mask:0xf bound_ctrl:1
	v_add_f32_dpp v199, v199, v199 quad_perm:[1,0,3,2] row_mask:0xf bank_mask:0xf bound_ctrl:1
	v_add_f32_dpp v200, v200, v200 quad_perm:[1,0,3,2] row_mask:0xf bank_mask:0xf bound_ctrl:1
	v_add_f32_dpp v201, v201, v201 quad_perm:[1,0,3,2] row_mask:0xf bank_mask:0xf bound_ctrl:1
	s_waitcnt lgkmcnt(10)
	v_pk_mul_f16 v113, v113, v66
	v_pk_mul_f16 v178, v178, v67
	v_pk_mul_f16 v177, v177, v68
	v_pk_mul_f16 v176, v176, v69
	v_pk_mul_f16 v175, v175, v70
	v_pk_mul_f16 v174, v174, v71
	v_pk_mul_f16 v161, v161, v72
	v_pk_mul_f16 v160, v160, v73
	v_pk_mul_f16 v228, v228, v66
	v_pk_mul_f16 v229, v229, v67
	v_pk_mul_f16 v230, v230, v68
	v_pk_mul_f16 v231, v231, v69
	v_pk_mul_f16 v232, v232, v70
	v_pk_mul_f16 v233, v233, v71
	v_pk_mul_f16 v234, v234, v72
	v_pk_mul_f16 v235, v235, v73
	v_add_f32_dpp v198, v198, v198 quad_perm:[2,3,0,1] row_mask:0xf bank_mask:0xf bound_ctrl:1
	v_add_f32_dpp v199, v199, v199 quad_perm:[2,3,0,1] row_mask:0xf bank_mask:0xf bound_ctrl:1
	v_add_f32_dpp v200, v200, v200 quad_perm:[2,3,0,1] row_mask:0xf bank_mask:0xf bound_ctrl:1
	v_add_f32_dpp v201, v201, v201 quad_perm:[2,3,0,1] row_mask:0xf bank_mask:0xf bound_ctrl:1
	s_waitcnt lgkmcnt(7)
	v_pk_fma_f16 v113, v115, v74, v113
	v_pk_fma_f16 v178, v115, v75, v178
	v_pk_fma_f16 v177, v115, v76, v177
	v_pk_fma_f16 v176, v115, v77, v176
	v_pk_fma_f16 v175, v115, v78, v175
	v_pk_fma_f16 v174, v115, v79, v174
	v_pk_fma_f16 v161, v115, v80, v161
	v_pk_fma_f16 v160, v115, v81, v160
	ds_read_b128 v[66:69], v202 offset:8576
	ds_read_b128 v[70:73], v202 offset:8592
	ds_read_b128 v[74:77], v202 offset:12672
	ds_read_b128 v[78:81], v202 offset:12688
	ds_read_b32 v115, v203 offset:21248
	v_cvt_pk_f16_f32 v198, v198, v199
	s_waitcnt lgkmcnt(15)
	v_pk_fma_f16 v113, v198, v82, v113 op_sel_hi:[0,1,1]
	v_pk_fma_f16 v228, v198, v82, v228 op_sel:[1,0,0] op_sel_hi:[1,1,1]
	v_pk_fma_f16 v178, v198, v83, v178 op_sel_hi:[0,1,1]
	v_pk_fma_f16 v229, v198, v83, v229 op_sel:[1,0,0] op_sel_hi:[1,1,1]
	v_pk_fma_f16 v177, v198, v84, v177 op_sel_hi:[0,1,1]
	v_pk_fma_f16 v230, v198, v84, v230 op_sel:[1,0,0] op_sel_hi:[1,1,1]
	v_pk_fma_f16 v176, v198, v85, v176 op_sel_hi:[0,1,1]
	v_pk_fma_f16 v231, v198, v85, v231 op_sel:[1,0,0] op_sel_hi:[1,1,1]
	v_pk_fma_f16 v175, v198, v86, v175 op_sel_hi:[0,1,1]
	v_pk_fma_f16 v232, v198, v86, v232 op_sel:[1,0,0] op_sel_hi:[1,1,1]
	v_pk_fma_f16 v174, v198, v87, v174 op_sel_hi:[0,1,1]
	v_pk_fma_f16 v233, v198, v87, v233 op_sel:[1,0,0] op_sel_hi:[1,1,1]
	v_pk_fma_f16 v161, v198, v88, v161 op_sel_hi:[0,1,1]
	v_pk_fma_f16 v234, v198, v88, v234 op_sel:[1,0,0] op_sel_hi:[1,1,1]
	v_pk_fma_f16 v160, v198, v89, v160 op_sel_hi:[0,1,1]
	v_pk_fma_f16 v235, v198, v89, v235 op_sel:[1,0,0] op_sel_hi:[1,1,1]
	s_and_saveexec_b64 s[30:31], s[98:99]
	ds_write2st64_b32 v203, v201, v200 offset0:113 offset1:145
	s_or_b64 exec, exec, s[30:31]
	s_waitcnt lgkmcnt(8)
	ds_read_b128 v[82:85], v202 offset:4608
	ds_read_b128 v[86:89], v202 offset:4624
	v_dot2_f32_f16 v198, v113, v58, 0
	v_dot2_f32_f16 v199, v228, v58, 0
	v_dot2_f32_f16 v200, v113, v182, 0
	v_dot2_f32_f16 v201, v228, v182, 0
	v_dot2_f32_f16 v198, v178, v59, v198
	v_dot2_f32_f16 v199, v229, v59, v199
	v_dot2_f32_f16 v200, v178, v183, v200
	v_dot2_f32_f16 v201, v229, v183, v201
	v_dot2_f32_f16 v198, v177, v60, v198
	v_dot2_f32_f16 v199, v230, v60, v199
	v_dot2_f32_f16 v200, v177, v184, v200
	v_dot2_f32_f16 v201, v230, v184, v201
	v_dot2_f32_f16 v198, v176, v61, v198
	v_dot2_f32_f16 v199, v231, v61, v199
	v_dot2_f32_f16 v200, v176, v185, v200
	v_dot2_f32_f16 v201, v231, v185, v201
	v_dot2_f32_f16 v198, v175, v62, v198
	v_dot2_f32_f16 v199, v232, v62, v199
	v_dot2_f32_f16 v200, v175, v186, v200
	v_dot2_f32_f16 v201, v232, v186, v201
	v_dot2_f32_f16 v198, v174, v63, v198
	v_dot2_f32_f16 v199, v233, v63, v199
	v_dot2_f32_f16 v200, v174, v187, v200
	v_dot2_f32_f16 v201, v233, v187, v201
	v_dot2_f32_f16 v198, v161, v64, v198
	v_dot2_f32_f16 v199, v234, v64, v199
	v_dot2_f32_f16 v200, v161, v188, v200
	v_dot2_f32_f16 v201, v234, v188, v201
	v_dot2_f32_f16 v198, v160, v65, v198
	v_dot2_f32_f16 v199, v235, v65, v199
	v_dot2_f32_f16 v200, v160, v189, v200
	v_dot2_f32_f16 v201, v235, v189, v201
	ds_read_b128 v[58:61], v202 offset:512
	ds_read_b128 v[62:65], v202 offset:528
	ds_read_b128 v[182:185], v202 offset:16896
	ds_read_b128 v[186:189], v202 offset:16912
	v_add_f32_dpp v198, v198, v198 quad_perm:[1,0,3,2] row_mask:0xf bank_mask:0xf bound_ctrl:1
	v_add_f32_dpp v199, v199, v199 quad_perm:[1,0,3,2] row_mask:0xf bank_mask:0xf bound_ctrl:1
	v_add_f32_dpp v200, v200, v200 quad_perm:[1,0,3,2] row_mask:0xf bank_mask:0xf bound_ctrl:1
	v_add_f32_dpp v201, v201, v201 quad_perm:[1,0,3,2] row_mask:0xf bank_mask:0xf bound_ctrl:1
	s_waitcnt lgkmcnt(10)
	v_pk_mul_f16 v113, v113, v66
	v_pk_mul_f16 v178, v178, v67
	v_pk_mul_f16 v177, v177, v68
	v_pk_mul_f16 v176, v176, v69
	v_pk_mul_f16 v175, v175, v70
	v_pk_mul_f16 v174, v174, v71
	v_pk_mul_f16 v161, v161, v72
	v_pk_mul_f16 v160, v160, v73
	v_pk_mul_f16 v228, v228, v66
	v_pk_mul_f16 v229, v229, v67
	v_pk_mul_f16 v230, v230, v68
	v_pk_mul_f16 v231, v231, v69
	v_pk_mul_f16 v232, v232, v70
	v_pk_mul_f16 v233, v233, v71
	v_pk_mul_f16 v234, v234, v72
	v_pk_mul_f16 v235, v235, v73
	v_add_f32_dpp v198, v198, v198 quad_perm:[2,3,0,1] row_mask:0xf bank_mask:0xf bound_ctrl:1
	v_add_f32_dpp v199, v199, v199 quad_perm:[2,3,0,1] row_mask:0xf bank_mask:0xf bound_ctrl:1
	v_add_f32_dpp v200, v200, v200 quad_perm:[2,3,0,1] row_mask:0xf bank_mask:0xf bound_ctrl:1
	v_add_f32_dpp v201, v201, v201 quad_perm:[2,3,0,1] row_mask:0xf bank_mask:0xf bound_ctrl:1
	s_waitcnt lgkmcnt(7)
	v_pk_fma_f16 v113, v115, v74, v113
	v_pk_fma_f16 v178, v115, v75, v178
	v_pk_fma_f16 v177, v115, v76, v177
	v_pk_fma_f16 v176, v115, v77, v176
	v_pk_fma_f16 v175, v115, v78, v175
	v_pk_fma_f16 v174, v115, v79, v174
	v_pk_fma_f16 v161, v115, v80, v161
	v_pk_fma_f16 v160, v115, v81, v160
	ds_read_b128 v[66:69], v202 offset:8704
	ds_read_b128 v[70:73], v202 offset:8720
	ds_read_b128 v[74:77], v202 offset:12800
	ds_read_b128 v[78:81], v202 offset:12816
	ds_read_b32 v115, v203 offset:21504
	v_cvt_pk_f16_f32 v198, v198, v199
	s_waitcnt lgkmcnt(15)
	v_pk_fma_f16 v113, v198, v90, v113 op_sel_hi:[0,1,1]
	v_pk_fma_f16 v228, v198, v90, v228 op_sel:[1,0,0] op_sel_hi:[1,1,1]
	v_pk_fma_f16 v178, v198, v91, v178 op_sel_hi:[0,1,1]
	v_pk_fma_f16 v229, v198, v91, v229 op_sel:[1,0,0] op_sel_hi:[1,1,1]
	v_pk_fma_f16 v177, v198, v92, v177 op_sel_hi:[0,1,1]
	v_pk_fma_f16 v230, v198, v92, v230 op_sel:[1,0,0] op_sel_hi:[1,1,1]
	v_pk_fma_f16 v176, v198, v93, v176 op_sel_hi:[0,1,1]
	v_pk_fma_f16 v231, v198, v93, v231 op_sel:[1,0,0] op_sel_hi:[1,1,1]
	v_pk_fma_f16 v175, v198, v94, v175 op_sel_hi:[0,1,1]
	v_pk_fma_f16 v232, v198, v94, v232 op_sel:[1,0,0] op_sel_hi:[1,1,1]
	v_pk_fma_f16 v174, v198, v95, v174 op_sel_hi:[0,1,1]
	v_pk_fma_f16 v233, v198, v95, v233 op_sel:[1,0,0] op_sel_hi:[1,1,1]
	v_pk_fma_f16 v161, v198, v96, v161 op_sel_hi:[0,1,1]
	v_pk_fma_f16 v234, v198, v96, v234 op_sel:[1,0,0] op_sel_hi:[1,1,1]
	v_pk_fma_f16 v160, v198, v97, v160 op_sel_hi:[0,1,1]
	v_pk_fma_f16 v235, v198, v97, v235 op_sel:[1,0,0] op_sel_hi:[1,1,1]
	s_and_saveexec_b64 s[30:31], s[98:99]
	ds_write2st64_b32 v203, v201, v200 offset0:114 offset1:146
	s_or_b64 exec, exec, s[30:31]
	s_waitcnt lgkmcnt(8)
	ds_read_b128 v[90:93], v202 offset:4736
	ds_read_b128 v[94:97], v202 offset:4752
	v_dot2_f32_f16 v198, v113, v58, 0
	v_dot2_f32_f16 v199, v228, v58, 0
	v_dot2_f32_f16 v200, v113, v190, 0
	v_dot2_f32_f16 v201, v228, v190, 0
	v_dot2_f32_f16 v198, v178, v59, v198
	v_dot2_f32_f16 v199, v229, v59, v199
	v_dot2_f32_f16 v200, v178, v191, v200
	v_dot2_f32_f16 v201, v229, v191, v201
	v_dot2_f32_f16 v198, v177, v60, v198
	v_dot2_f32_f16 v199, v230, v60, v199
	v_dot2_f32_f16 v200, v177, v192, v200
	v_dot2_f32_f16 v201, v230, v192, v201
	v_dot2_f32_f16 v198, v176, v61, v198
	v_dot2_f32_f16 v199, v231, v61, v199
	v_dot2_f32_f16 v200, v176, v193, v200
	v_dot2_f32_f16 v201, v231, v193, v201
	v_dot2_f32_f16 v198, v175, v62, v198
	v_dot2_f32_f16 v199, v232, v62, v199
	v_dot2_f32_f16 v200, v175, v194, v200
	v_dot2_f32_f16 v201, v232, v194, v201
	v_dot2_f32_f16 v198, v174, v63, v198
	v_dot2_f32_f16 v199, v233, v63, v199
	v_dot2_f32_f16 v200, v174, v195, v200
	v_dot2_f32_f16 v201, v233, v195, v201
	v_dot2_f32_f16 v198, v161, v64, v198
	v_dot2_f32_f16 v199, v234, v64, v199
	v_dot2_f32_f16 v200, v161, v196, v200
	v_dot2_f32_f16 v201, v234, v196, v201
	v_dot2_f32_f16 v198, v160, v65, v198
	v_dot2_f32_f16 v199, v235, v65, v199
	v_dot2_f32_f16 v200, v160, v197, v200
	v_dot2_f32_f16 v201, v235, v197, v201
	ds_read_b128 v[58:61], v202 offset:640
	ds_read_b128 v[62:65], v202 offset:656
	ds_read_b128 v[190:193], v202 offset:17024
	ds_read_b128 v[194:197], v202 offset:17040
	v_add_f32_dpp v198, v198, v198 quad_perm:[1,0,3,2] row_mask:0xf bank_mask:0xf bound_ctrl:1
	v_add_f32_dpp v199, v199, v199 quad_perm:[1,0,3,2] row_mask:0xf bank_mask:0xf bound_ctrl:1
	v_add_f32_dpp v200, v200, v200 quad_perm:[1,0,3,2] row_mask:0xf bank_mask:0xf bound_ctrl:1
	v_add_f32_dpp v201, v201, v201 quad_perm:[1,0,3,2] row_mask:0xf bank_mask:0xf bound_ctrl:1
	s_waitcnt lgkmcnt(10)
	v_pk_mul_f16 v113, v113, v66
	v_pk_mul_f16 v178, v178, v67
	v_pk_mul_f16 v177, v177, v68
	v_pk_mul_f16 v176, v176, v69
	v_pk_mul_f16 v175, v175, v70
	v_pk_mul_f16 v174, v174, v71
	v_pk_mul_f16 v161, v161, v72
	v_pk_mul_f16 v160, v160, v73
	v_pk_mul_f16 v228, v228, v66
	v_pk_mul_f16 v229, v229, v67
	v_pk_mul_f16 v230, v230, v68
	v_pk_mul_f16 v231, v231, v69
	v_pk_mul_f16 v232, v232, v70
	v_pk_mul_f16 v233, v233, v71
	v_pk_mul_f16 v234, v234, v72
	v_pk_mul_f16 v235, v235, v73
	v_add_f32_dpp v198, v198, v198 quad_perm:[2,3,0,1] row_mask:0xf bank_mask:0xf bound_ctrl:1
	v_add_f32_dpp v199, v199, v199 quad_perm:[2,3,0,1] row_mask:0xf bank_mask:0xf bound_ctrl:1
	v_add_f32_dpp v200, v200, v200 quad_perm:[2,3,0,1] row_mask:0xf bank_mask:0xf bound_ctrl:1
	v_add_f32_dpp v201, v201, v201 quad_perm:[2,3,0,1] row_mask:0xf bank_mask:0xf bound_ctrl:1
	s_waitcnt lgkmcnt(7)
	v_pk_fma_f16 v113, v115, v74, v113
	v_pk_fma_f16 v178, v115, v75, v178
	v_pk_fma_f16 v177, v115, v76, v177
	v_pk_fma_f16 v176, v115, v77, v176
	v_pk_fma_f16 v175, v115, v78, v175
	v_pk_fma_f16 v174, v115, v79, v174
	v_pk_fma_f16 v161, v115, v80, v161
	v_pk_fma_f16 v160, v115, v81, v160
	ds_read_b128 v[66:69], v202 offset:8832
	ds_read_b128 v[70:73], v202 offset:8848
	ds_read_b128 v[74:77], v202 offset:12928
	ds_read_b128 v[78:81], v202 offset:12944
	ds_read_b32 v115, v203 offset:21760
	v_cvt_pk_f16_f32 v198, v198, v199
	s_waitcnt lgkmcnt(15)
	v_pk_fma_f16 v113, v198, v82, v113 op_sel_hi:[0,1,1]
	v_pk_fma_f16 v228, v198, v82, v228 op_sel:[1,0,0] op_sel_hi:[1,1,1]
	v_pk_fma_f16 v178, v198, v83, v178 op_sel_hi:[0,1,1]
	v_pk_fma_f16 v229, v198, v83, v229 op_sel:[1,0,0] op_sel_hi:[1,1,1]
	v_pk_fma_f16 v177, v198, v84, v177 op_sel_hi:[0,1,1]
	v_pk_fma_f16 v230, v198, v84, v230 op_sel:[1,0,0] op_sel_hi:[1,1,1]
	v_pk_fma_f16 v176, v198, v85, v176 op_sel_hi:[0,1,1]
	v_pk_fma_f16 v231, v198, v85, v231 op_sel:[1,0,0] op_sel_hi:[1,1,1]
	v_pk_fma_f16 v175, v198, v86, v175 op_sel_hi:[0,1,1]
	v_pk_fma_f16 v232, v198, v86, v232 op_sel:[1,0,0] op_sel_hi:[1,1,1]
	v_pk_fma_f16 v174, v198, v87, v174 op_sel_hi:[0,1,1]
	v_pk_fma_f16 v233, v198, v87, v233 op_sel:[1,0,0] op_sel_hi:[1,1,1]
	v_pk_fma_f16 v161, v198, v88, v161 op_sel_hi:[0,1,1]
	v_pk_fma_f16 v234, v198, v88, v234 op_sel:[1,0,0] op_sel_hi:[1,1,1]
	v_pk_fma_f16 v160, v198, v89, v160 op_sel_hi:[0,1,1]
	v_pk_fma_f16 v235, v198, v89, v235 op_sel:[1,0,0] op_sel_hi:[1,1,1]
	s_and_saveexec_b64 s[30:31], s[98:99]
	ds_write2st64_b32 v203, v201, v200 offset0:115 offset1:147
	s_or_b64 exec, exec, s[30:31]
	s_add_i32 s37, s37, 1
	v_add_u32_e32 v202, 0x200, v202
	v_add_u32_e32 v203, 0x400, v203
	s_cmp_lg_u32 s37, 7
	s_cbranch_scc1 .LscanH_loop
	s_waitcnt lgkmcnt(8)
	ds_read_b128 v[82:85], v202 offset:4352
	ds_read_b128 v[86:89], v202 offset:4368
	v_dot2_f32_f16 v198, v113, v58, 0
	v_dot2_f32_f16 v199, v228, v58, 0
	v_dot2_f32_f16 v200, v113, v182, 0
	v_dot2_f32_f16 v201, v228, v182, 0
	v_dot2_f32_f16 v198, v178, v59, v198
	v_dot2_f32_f16 v199, v229, v59, v199
	v_dot2_f32_f16 v200, v178, v183, v200
	v_dot2_f32_f16 v201, v229, v183, v201
	v_dot2_f32_f16 v198, v177, v60, v198
	v_dot2_f32_f16 v199, v230, v60, v199
	v_dot2_f32_f16 v200, v177, v184, v200
	v_dot2_f32_f16 v201, v230, v184, v201
	v_dot2_f32_f16 v198, v176, v61, v198
	v_dot2_f32_f16 v199, v231, v61, v199
	v_dot2_f32_f16 v200, v176, v185, v200
	v_dot2_f32_f16 v201, v231, v185, v201
	v_dot2_f32_f16 v198, v175, v62, v198
	v_dot2_f32_f16 v199, v232, v62, v199
	v_dot2_f32_f16 v200, v175, v186, v200
	v_dot2_f32_f16 v201, v232, v186, v201
	v_dot2_f32_f16 v198, v174, v63, v198
	v_dot2_f32_f16 v199, v233, v63, v199
	v_dot2_f32_f16 v200, v174, v187, v200
	v_dot2_f32_f16 v201, v233, v187, v201
	v_dot2_f32_f16 v198, v161, v64, v198
	v_dot2_f32_f16 v199, v234, v64, v199
	v_dot2_f32_f16 v200, v161, v188, v200
	v_dot2_f32_f16 v201, v234, v188, v201
	v_dot2_f32_f16 v198, v160, v65, v198
	v_dot2_f32_f16 v199, v235, v65, v199
	v_dot2_f32_f16 v200, v160, v189, v200
	v_dot2_f32_f16 v201, v235, v189, v201
	ds_read_b128 v[58:61], v202 offset:256
	ds_read_b128 v[62:65], v202 offset:272
	ds_read_b128 v[182:185], v202 offset:16640
	ds_read_b128 v[186:189], v202 offset:16656
	v_add_f32_dpp v198, v198, v198 quad_perm:[1,0,3,2] row_mask:0xf bank_mask:0xf bound_ctrl:1
	v_add_f32_dpp v199, v199, v199 quad_perm:[1,0,3,2] row_mask:0xf bank_mask:0xf bound_ctrl:1
	v_add_f32_dpp v200, v200, v200 quad_perm:[1,0,3,2] row_mask:0xf bank_mask:0xf bound_ctrl:1
	v_add_f32_dpp v201, v201, v201 quad_perm:[1,0,3,2] row_mask:0xf bank_mask:0xf bound_ctrl:1
	s_waitcnt lgkmcnt(10)
	v_pk_mul_f16 v113, v113, v66
	v_pk_mul_f16 v178, v178, v67
	v_pk_mul_f16 v177, v177, v68
	v_pk_mul_f16 v176, v176, v69
	v_pk_mul_f16 v175, v175, v70
	v_pk_mul_f16 v174, v174, v71
	v_pk_mul_f16 v161, v161, v72
	v_pk_mul_f16 v160, v160, v73
	v_pk_mul_f16 v228, v228, v66
	v_pk_mul_f16 v229, v229, v67
	v_pk_mul_f16 v230, v230, v68
	v_pk_mul_f16 v231, v231, v69
	v_pk_mul_f16 v232, v232, v70
	v_pk_mul_f16 v233, v233, v71
	v_pk_mul_f16 v234, v234, v72
	v_pk_mul_f16 v235, v235, v73
	v_add_f32_dpp v198, v198, v198 quad_perm:[2,3,0,1] row_mask:0xf bank_mask:0xf bound_ctrl:1
	v_add_f32_dpp v199, v199, v199 quad_perm:[2,3,0,1] row_mask:0xf bank_mask:0xf bound_ctrl:1
	v_add_f32_dpp v200, v200, v200 quad_perm:[2,3,0,1] row_mask:0xf bank_mask:0xf bound_ctrl:1
	v_add_f32_dpp v201, v201, v201 quad_perm:[2,3,0,1] row_mask:0xf bank_mask:0xf bound_ctrl:1
	s_waitcnt lgkmcnt(7)
	v_pk_fma_f16 v113, v115, v74, v113
	v_pk_fma_f16 v178, v115, v75, v178
	v_pk_fma_f16 v177, v115, v76, v177
	v_pk_fma_f16 v176, v115, v77, v176
	v_pk_fma_f16 v175, v115, v78, v175
	v_pk_fma_f16 v174, v115, v79, v174
	v_pk_fma_f16 v161, v115, v80, v161
	v_pk_fma_f16 v160, v115, v81, v160
	ds_read_b128 v[66:69], v202 offset:8448
	ds_read_b128 v[70:73], v202 offset:8464
	ds_read_b128 v[74:77], v202 offset:12544
	ds_read_b128 v[78:81], v202 offset:12560
	ds_read_b32 v115, v203 offset:20992
	v_cvt_pk_f16_f32 v198, v198, v199
	s_waitcnt lgkmcnt(15)
	v_pk_fma_f16 v113, v198, v90, v113 op_sel_hi:[0,1,1]
	v_pk_fma_f16 v228, v198, v90, v228 op_sel:[1,0,0] op_sel_hi:[1,1,1]
	v_pk_fma_f16 v178, v198, v91, v178 op_sel_hi:[0,1,1]
	v_pk_fma_f16 v229, v198, v91, v229 op_sel:[1,0,0] op_sel_hi:[1,1,1]
	v_pk_fma_f16 v177, v198, v92, v177 op_sel_hi:[0,1,1]
	v_pk_fma_f16 v230, v198, v92, v230 op_sel:[1,0,0] op_sel_hi:[1,1,1]
	v_pk_fma_f16 v176, v198, v93, v176 op_sel_hi:[0,1,1]
	v_pk_fma_f16 v231, v198, v93, v231 op_sel:[1,0,0] op_sel_hi:[1,1,1]
	v_pk_fma_f16 v175, v198, v94, v175 op_sel_hi:[0,1,1]
	v_pk_fma_f16 v232, v198, v94, v232 op_sel:[1,0,0] op_sel_hi:[1,1,1]
	v_pk_fma_f16 v174, v198, v95, v174 op_sel_hi:[0,1,1]
	v_pk_fma_f16 v233, v198, v95, v233 op_sel:[1,0,0] op_sel_hi:[1,1,1]
	v_pk_fma_f16 v161, v198, v96, v161 op_sel_hi:[0,1,1]
	v_pk_fma_f16 v234, v198, v96, v234 op_sel:[1,0,0] op_sel_hi:[1,1,1]
	v_pk_fma_f16 v160, v198, v97, v160 op_sel_hi:[0,1,1]
	v_pk_fma_f16 v235, v198, v97, v235 op_sel:[1,0,0] op_sel_hi:[1,1,1]
	s_and_saveexec_b64 s[30:31], s[98:99]
	ds_write2st64_b32 v203, v201, v200 offset0:112 offset1:144
	s_or_b64 exec, exec, s[30:31]
	s_waitcnt lgkmcnt(8)
	ds_read_b128 v[90:93], v202 offset:4480
	ds_read_b128 v[94:97], v202 offset:4496
	v_dot2_f32_f16 v198, v113, v58, 0
	v_dot2_f32_f16 v199, v228, v58, 0
	v_dot2_f32_f16 v200, v113, v190, 0
	v_dot2_f32_f16 v201, v228, v190, 0
	v_dot2_f32_f16 v198, v178, v59, v198
	v_dot2_f32_f16 v199, v229, v59, v199
	v_dot2_f32_f16 v200, v178, v191, v200
	v_dot2_f32_f16 v201, v229, v191, v201
	v_dot2_f32_f16 v198, v177, v60, v198
	v_dot2_f32_f16 v199, v230, v60, v199
	v_dot2_f32_f16 v200, v177, v192, v200
	v_dot2_f32_f16 v201, v230, v192, v201
	v_dot2_f32_f16 v198, v176, v61, v198
	v_dot2_f32_f16 v199, v231, v61, v199
	v_dot2_f32_f16 v200, v176, v193, v200
	v_dot2_f32_f16 v201, v231, v193, v201
	v_dot2_f32_f16 v198, v175, v62, v198
	v_dot2_f32_f16 v199, v232, v62, v199
	v_dot2_f32_f16 v200, v175, v194, v200
	v_dot2_f32_f16 v201, v232, v194, v201
	v_dot2_f32_f16 v198, v174, v63, v198
	v_dot2_f32_f16 v199, v233, v63, v199
	v_dot2_f32_f16 v200, v174, v195, v200
	v_dot2_f32_f16 v201, v233, v195, v201
	v_dot2_f32_f16 v198, v161, v64, v198
	v_dot2_f32_f16 v199, v234, v64, v199
	v_dot2_f32_f16 v200, v161, v196, v200
	v_dot2_f32_f16 v201, v234, v196, v201
	v_dot2_f32_f16 v198, v160, v65, v198
	v_dot2_f32_f16 v199, v235, v65, v199
	v_dot2_f32_f16 v200, v160, v197, v200
	v_dot2_f32_f16 v201, v235, v197, v201
	ds_read_b128 v[58:61], v202 offset:384
	ds_read_b128 v[62:65], v202 offset:400
	ds_read_b128 v[190:193], v202 offset:16768
	ds_read_b128 v[194:197], v202 offset:16784
	v_add_f32_dpp v198, v198, v198 quad_perm:[1,0,3,2] row_mask:0xf bank_mask:0xf bound_ctrl:1
	v_add_f32_dpp v199, v199, v199 quad_perm:[1,0,3,2] row_mask:0xf bank_mask:0xf bound_ctrl:1
	v_add_f32_dpp v200, v200, v200 quad_perm:[1,0,3,2] row_mask:0xf bank_mask:0xf bound_ctrl:1
	v_add_f32_dpp v201, v201, v201 quad_perm:[1,0,3,2] row_mask:0xf bank_mask:0xf bound_ctrl:1
	s_waitcnt lgkmcnt(10)
	v_pk_mul_f16 v113, v113, v66
	v_pk_mul_f16 v178, v178, v67
	v_pk_mul_f16 v177, v177, v68
	v_pk_mul_f16 v176, v176, v69
	v_pk_mul_f16 v175, v175, v70
	v_pk_mul_f16 v174, v174, v71
	v_pk_mul_f16 v161, v161, v72
	v_pk_mul_f16 v160, v160, v73
	v_pk_mul_f16 v228, v228, v66
	v_pk_mul_f16 v229, v229, v67
	v_pk_mul_f16 v230, v230, v68
	v_pk_mul_f16 v231, v231, v69
	v_pk_mul_f16 v232, v232, v70
	v_pk_mul_f16 v233, v233, v71
	v_pk_mul_f16 v234, v234, v72
	v_pk_mul_f16 v235, v235, v73
	v_add_f32_dpp v198, v198, v198 quad_perm:[2,3,0,1] row_mask:0xf bank_mask:0xf bound_ctrl:1
	v_add_f32_dpp v199, v199, v199 quad_perm:[2,3,0,1] row_mask:0xf bank_mask:0xf bound_ctrl:1
	v_add_f32_dpp v200, v200, v200 quad_perm:[2,3,0,1] row_mask:0xf bank_mask:0xf bound_ctrl:1
	v_add_f32_dpp v201, v201, v201 quad_perm:[2,3,0,1] row_mask:0xf bank_mask:0xf bound_ctrl:1
	s_waitcnt lgkmcnt(7)
	v_pk_fma_f16 v113, v115, v74, v113
	v_pk_fma_f16 v178, v115, v75, v178
	v_pk_fma_f16 v177, v115, v76, v177
	v_pk_fma_f16 v176, v115, v77, v176
	v_pk_fma_f16 v175, v115, v78, v175
	v_pk_fma_f16 v174, v115, v79, v174
	v_pk_fma_f16 v161, v115, v80, v161
	v_pk_fma_f16 v160, v115, v81, v160
	ds_read_b128 v[66:69], v202 offset:8576
	ds_read_b128 v[70:73], v202 offset:8592
	ds_read_b128 v[74:77], v202 offset:12672
	ds_read_b128 v[78:81], v202 offset:12688
	ds_read_b32 v115, v203 offset:21248
	v_cvt_pk_f16_f32 v198, v198, v199
	s_waitcnt lgkmcnt(15)
	v_pk_fma_f16 v113, v198, v82, v113 op_sel_hi:[0,1,1]
	v_pk_fma_f16 v228, v198, v82, v228 op_sel:[1,0,0] op_sel_hi:[1,1,1]
	v_pk_fma_f16 v178, v198, v83, v178 op_sel_hi:[0,1,1]
	v_pk_fma_f16 v229, v198, v83, v229 op_sel:[1,0,0] op_sel_hi:[1,1,1]
	v_pk_fma_f16 v177, v198, v84, v177 op_sel_hi:[0,1,1]
	v_pk_fma_f16 v230, v198, v84, v230 op_sel:[1,0,0] op_sel_hi:[1,1,1]
	v_pk_fma_f16 v176, v198, v85, v176 op_sel_hi:[0,1,1]
	v_pk_fma_f16 v231, v198, v85, v231 op_sel:[1,0,0] op_sel_hi:[1,1,1]
	v_pk_fma_f16 v175, v198, v86, v175 op_sel_hi:[0,1,1]
	v_pk_fma_f16 v232, v198, v86, v232 op_sel:[1,0,0] op_sel_hi:[1,1,1]
	v_pk_fma_f16 v174, v198, v87, v174 op_sel_hi:[0,1,1]
	v_pk_fma_f16 v233, v198, v87, v233 op_sel:[1,0,0] op_sel_hi:[1,1,1]
	v_pk_fma_f16 v161, v198, v88, v161 op_sel_hi:[0,1,1]
	v_pk_fma_f16 v234, v198, v88, v234 op_sel:[1,0,0] op_sel_hi:[1,1,1]
	v_pk_fma_f16 v160, v198, v89, v160 op_sel_hi:[0,1,1]
	v_pk_fma_f16 v235, v198, v89, v235 op_sel:[1,0,0] op_sel_hi:[1,1,1]
	s_and_saveexec_b64 s[30:31], s[98:99]
	ds_write2st64_b32 v203, v201, v200 offset0:113 offset1:145
	s_or_b64 exec, exec, s[30:31]
	s_waitcnt lgkmcnt(8)
	v_dot2_f32_f16 v198, v113, v58, 0
	v_dot2_f32_f16 v199, v228, v58, 0
	v_dot2_f32_f16 v200, v113, v182, 0
	v_dot2_f32_f16 v201, v228, v182, 0
	v_dot2_f32_f16 v198, v178, v59, v198
	v_dot2_f32_f16 v199, v229, v59, v199
	v_dot2_f32_f16 v200, v178, v183, v200
	v_dot2_f32_f16 v201, v229, v183, v201
	v_dot2_f32_f16 v198, v177, v60, v198
	v_dot2_f32_f16 v199, v230, v60, v199
	v_dot2_f32_f16 v200, v177, v184, v200
	v_dot2_f32_f16 v201, v230, v184, v201
	v_dot2_f32_f16 v198, v176, v61, v198
	v_dot2_f32_f16 v199, v231, v61, v199
	v_dot2_f32_f16 v200, v176, v185, v200
	v_dot2_f32_f16 v201, v231, v185, v201
	v_dot2_f32_f16 v198, v175, v62, v198
	v_dot2_f32_f16 v199, v232, v62, v199
	v_dot2_f32_f16 v200, v175, v186, v200
	v_dot2_f32_f16 v201, v232, v186, v201
	v_dot2_f32_f16 v198, v174, v63, v198
	v_dot2_f32_f16 v199, v233, v63, v199
	v_dot2_f32_f16 v200, v174, v187, v200
	v_dot2_f32_f16 v201, v233, v187, v201
	v_dot2_f32_f16 v198, v161, v64, v198
	v_dot2_f32_f16 v199, v234, v64, v199
	v_dot2_f32_f16 v200, v161, v188, v200
	v_dot2_f32_f16 v201, v234, v188, v201
	v_dot2_f32_f16 v198, v160, v65, v198
	v_dot2_f32_f16 v199, v235, v65, v199
	v_dot2_f32_f16 v200, v160, v189, v200
	v_dot2_f32_f16 v201, v235, v189, v201
	s_nop 2
	v_add_f32_dpp v198, v198, v198 quad_perm:[1,0,3,2] row_mask:0xf bank_mask:0xf bound_ctrl:1
	v_add_f32_dpp v199, v199, v199 quad_perm:[1,0,3,2] row_mask:0xf bank_mask:0xf bound_ctrl:1
	v_add_f32_dpp v200, v200, v200 quad_perm:[1,0,3,2] row_mask:0xf bank_mask:0xf bound_ctrl:1
	v_add_f32_dpp v201, v201, v201 quad_perm:[1,0,3,2] row_mask:0xf bank_mask:0xf bound_ctrl:1
	s_waitcnt lgkmcnt(4)
	v_pk_mul_f16 v113, v113, v66
	v_pk_mul_f16 v178, v178, v67
	v_pk_mul_f16 v177, v177, v68
	v_pk_mul_f16 v176, v176, v69
	v_pk_mul_f16 v175, v175, v70
	v_pk_mul_f16 v174, v174, v71
	v_pk_mul_f16 v161, v161, v72
	v_pk_mul_f16 v160, v160, v73
	v_pk_mul_f16 v228, v228, v66
	v_pk_mul_f16 v229, v229, v67
	v_pk_mul_f16 v230, v230, v68
	v_pk_mul_f16 v231, v231, v69
	v_pk_mul_f16 v232, v232, v70
	v_pk_mul_f16 v233, v233, v71
	v_pk_mul_f16 v234, v234, v72
	v_pk_mul_f16 v235, v235, v73
	v_add_f32_dpp v198, v198, v198 quad_perm:[2,3,0,1] row_mask:0xf bank_mask:0xf bound_ctrl:1
	v_add_f32_dpp v199, v199, v199 quad_perm:[2,3,0,1] row_mask:0xf bank_mask:0xf bound_ctrl:1
	v_add_f32_dpp v200, v200, v200 quad_perm:[2,3,0,1] row_mask:0xf bank_mask:0xf bound_ctrl:1
	v_add_f32_dpp v201, v201, v201 quad_perm:[2,3,0,1] row_mask:0xf bank_mask:0xf bound_ctrl:1
	s_waitcnt lgkmcnt(1)
	v_pk_fma_f16 v113, v115, v74, v113
	v_pk_fma_f16 v178, v115, v75, v178
	v_pk_fma_f16 v177, v115, v76, v177
	v_pk_fma_f16 v176, v115, v77, v176
	v_pk_fma_f16 v175, v115, v78, v175
	v_pk_fma_f16 v174, v115, v79, v174
	v_pk_fma_f16 v161, v115, v80, v161
	v_pk_fma_f16 v160, v115, v81, v160
	v_cvt_pk_f16_f32 v198, v198, v199
	s_waitcnt lgkmcnt(10)
	v_pk_fma_f16 v113, v198, v90, v113 op_sel_hi:[0,1,1]
	v_pk_fma_f16 v228, v198, v90, v228 op_sel:[1,0,0] op_sel_hi:[1,1,1]
	v_pk_fma_f16 v178, v198, v91, v178 op_sel_hi:[0,1,1]
	v_pk_fma_f16 v229, v198, v91, v229 op_sel:[1,0,0] op_sel_hi:[1,1,1]
	v_pk_fma_f16 v177, v198, v92, v177 op_sel_hi:[0,1,1]
	v_pk_fma_f16 v230, v198, v92, v230 op_sel:[1,0,0] op_sel_hi:[1,1,1]
	v_pk_fma_f16 v176, v198, v93, v176 op_sel_hi:[0,1,1]
	v_pk_fma_f16 v231, v198, v93, v231 op_sel:[1,0,0] op_sel_hi:[1,1,1]
	v_pk_fma_f16 v175, v198, v94, v175 op_sel_hi:[0,1,1]
	v_pk_fma_f16 v232, v198, v94, v232 op_sel:[1,0,0] op_sel_hi:[1,1,1]
	v_pk_fma_f16 v174, v198, v95, v174 op_sel_hi:[0,1,1]
	v_pk_fma_f16 v233, v198, v95, v233 op_sel:[1,0,0] op_sel_hi:[1,1,1]
	v_pk_fma_f16 v161, v198, v96, v161 op_sel_hi:[0,1,1]
	v_pk_fma_f16 v234, v198, v96, v234 op_sel:[1,0,0] op_sel_hi:[1,1,1]
	v_pk_fma_f16 v160, v198, v97, v160 op_sel_hi:[0,1,1]
	v_pk_fma_f16 v235, v198, v97, v235 op_sel:[1,0,0] op_sel_hi:[1,1,1]
	s_and_saveexec_b64 s[30:31], s[98:99]
	ds_write2st64_b32 v203, v201, v200 offset0:114 offset1:146
	s_or_b64 exec, exec, s[30:31]
	s_waitcnt lgkmcnt(1)
	v_dot2_f32_f16 v200, v113, v190, 0
	v_dot2_f32_f16 v201, v228, v190, 0
	v_dot2_f32_f16 v200, v178, v191, v200
	v_dot2_f32_f16 v201, v229, v191, v201
	v_dot2_f32_f16 v200, v177, v192, v200
	v_dot2_f32_f16 v201, v230, v192, v201
	v_dot2_f32_f16 v200, v176, v193, v200
	v_dot2_f32_f16 v201, v231, v193, v201
	v_dot2_f32_f16 v200, v175, v194, v200
	v_dot2_f32_f16 v201, v232, v194, v201
	v_dot2_f32_f16 v200, v174, v195, v200
	v_dot2_f32_f16 v201, v233, v195, v201
	v_dot2_f32_f16 v200, v161, v196, v200
	v_dot2_f32_f16 v201, v234, v196, v201
	v_dot2_f32_f16 v200, v160, v197, v200
	v_dot2_f32_f16 v201, v235, v197, v201
	s_nop 2
	v_add_f32_dpp v200, v200, v200 quad_perm:[1,0,3,2] row_mask:0xf bank_mask:0xf bound_ctrl:1
	v_add_f32_dpp v201, v201, v201 quad_perm:[1,0,3,2] row_mask:0xf bank_mask:0xf bound_ctrl:1
	s_nop 1
	v_add_f32_dpp v200, v200, v200 quad_perm:[2,3,0,1] row_mask:0xf bank_mask:0xf bound_ctrl:1
	v_add_f32_dpp v201, v201, v201 quad_perm:[2,3,0,1] row_mask:0xf bank_mask:0xf bound_ctrl:1
	s_and_saveexec_b64 s[30:31], s[98:99]
	ds_write2st64_b32 v203, v201, v200 offset0:115 offset1:147
	s_or_b64 exec, exec, s[30:31]
